# NA loop QK^T: the 8 K-fragment LDS reads issued together with counted waits (was read-wait-MFMA serial)
# baseline (speedup 1.0000x reference)
; #define MFMA32(a, b, c) __builtin_amdgcn_mfma_f32_32x32x16_bf16(__builtin_bit_cast(bf16x8, (a)), __builtin_bit_cast(bf16x8, (b)), (c), 0, 0, 0)
; DI float ex2(float x) { return __builtin_amdgcn_exp2f(x); }
; DI int crow(int reg, int h) { return (reg & 3) + 8 * (reg >> 2) + 4 * h; }
; template <int DQK, bool NA>
; DI void attn_unit(const bf16_t* __restrict__ Qb, int ldq, const bf16_t* __restrict__ Kb, int ldk, const bf16_t* __restrict__ Vt,
;                   bf16_t* __restrict__ Ob, int ldo, int u, float sc, const float* __restrict__ rpb_h, char* smem) {
;     ...
;     if (active) {
;       const bf16_t* cK = sK + cur * 64 * KS + r * KS + 8 * h;
;       const bf16_t* cV = sV + cur * 64 * 72 + r * 72 + 8 * h;
;       f32x16 s0, s1;
;       {
;         const f32x16 zero16 = {0.f, 0.f, 0.f, 0.f, 0.f, 0.f, 0.f, 0.f, 0.f, 0.f, 0.f, 0.f, 0.f, 0.f, 0.f, 0.f};
;         u32x4 k0 = *(const u32x4*)(cK);
;         u32x4 k1 = *(const u32x4*)(cK + 32 * KS);
;         s0 = MFMA32(k0, qf[0], zero16);
;         s1 = MFMA32(k1, qf[0], zero16);
;       }
; #pragma unroll
;       for (int ds = 1; ds < NDS; ++ds) {
;         u32x4 k0 = *(const u32x4*)(cK + ds * 16);
;         u32x4 k1 = *(const u32x4*)(cK + 32 * KS + ds * 16);
;         s0 = MFMA32(k0, qf[ds], s0);
;         s1 = MFMA32(k1, qf[ds], s1);
;       }
;       if (NA) {
;         const int brow = (kt - rq + 7) * 31;
; #pragma unroll
;         for (int q = 0; q < 16; ++q) {
;           int kc0 = crow(q, h), kc1 = 32 + kc0;
;           bool v0 = (kc0 >= cs) && (kc0 < cs + 16), v1 = (kc1 >= cs) && (kc1 < cs + 16);
;           float b0 = v0 ? sBias[brow + kc0 - cq + 15] : 0.f;
;           float b1 = v1 ? sBias[brow + kc1 - cq + 15] : 0.f;
;           s0[q] = v0 ? (s0[q] * sc + b0) : -INFINITY;
;           s1[q] = v1 ? (s1[q] * sc + b1) : -INFINITY;
;         }
;       }
;       float mx = s0[0];
; #pragma unroll
;       for (int q = 1; q < 16; ++q) mx = fmaxf(mx, s0[q]);
; #pragma unroll
;       for (int q = 0; q < 16; ++q) mx = fmaxf(mx, s1[q]);
;       mx = fmaxf(mx, __shfl_xor(mx, 32));
;       if (__builtin_amdgcn_ballot_w64((mx - m_run) > 8.f) != 0ull) {
;         const float m_new = fmaxf(m_run, mx);
;         const float alpha = ex2(m_run - m_new);
;         m_run = m_new;
;         l_run *= alpha;
; #pragma unroll
;         for (int q = 0; q < 16; ++q) { o0[q] *= alpha; o1[q] *= alpha; }
;       }
.LBB0_296:
	v_cmp_ge_u32_e32 vcc, s97, v137
	v_cmp_lt_u32_e64 s[88:89], s97, v138
	s_and_b32 s1, s97, 1
	s_and_b64 vcc, vcc, s[88:89]
	s_and_saveexec_b64 s[88:89], vcc
	s_cbranch_execz .LBB0_360
	s_mul_i32 s4, s1, 0x2400
	v_add_u32_e32 v0, s4, v139
	ds_read_b128 v[160:163], v0
	ds_read_b128 v[164:167], v0 offset:4608
	ds_read_b128 v[168:171], v0 offset:32
	ds_read_b128 v[172:175], v0 offset:4640
	ds_read_b128 v[176:179], v0 offset:64
	ds_read_b128 v[180:183], v0 offset:4672
	ds_read_b128 v[184:187], v0 offset:96
	ds_read_b128 v[188:191], v0 offset:4704
	s_waitcnt lgkmcnt(7)
	v_mfma_f32_32x32x16_bf16 v[64:79], v[160:163], v[80:83], 0
	s_waitcnt lgkmcnt(6)
	v_mfma_f32_32x32x16_bf16 v[48:63], v[164:167], v[80:83], 0
	s_waitcnt lgkmcnt(5)
	v_mfma_f32_32x32x16_bf16 v[64:79], v[168:171], v[84:87], v[64:79]
	s_waitcnt lgkmcnt(4)
	v_mfma_f32_32x32x16_bf16 v[48:63], v[172:175], v[84:87], v[48:63]
	s_waitcnt lgkmcnt(3)
	v_mfma_f32_32x32x16_bf16 v[64:79], v[176:179], v[88:91], v[64:79]
	s_waitcnt lgkmcnt(2)
	v_mfma_f32_32x32x16_bf16 v[48:63], v[180:183], v[88:91], v[48:63]
	s_waitcnt lgkmcnt(1)
	v_mfma_f32_32x32x16_bf16 v[64:79], v[184:187], v[92:95], v[64:79]
	s_waitcnt lgkmcnt(0)
	v_mfma_f32_32x32x16_bf16 v[48:63], v[188:191], v[92:95], v[48:63]
	ds_read_b32 v3, v141
	ds_read_b32 v117, v141 offset:128
	ds_read_b32 v5, v141 offset:4
	ds_read_b32 v142, v141 offset:132
	ds_read_b32 v143, v141 offset:8
	ds_read_b32 v144, v141 offset:136
	ds_read_b32 v145, v141 offset:12
	ds_read_b32 v146, v141 offset:140
	ds_read_b32 v147, v141 offset:32
	ds_read_b32 v148, v141 offset:160
	ds_read_b32 v149, v141 offset:36
	ds_read_b32 v150, v141 offset:164
	ds_read_b32 v151, v141 offset:40
	ds_read_b32 v152, v141 offset:168
	ds_read_b32 v153, v141 offset:44
	ds_read_b32 v154, v141 offset:172
	ds_read_b32 v14, v141 offset:64
	ds_read_b32 v155, v141 offset:192
	ds_read_b32 v15, v141 offset:68
	ds_read_b32 v156, v141 offset:196
	ds_read_b32 v10, v141 offset:72
	ds_read_b32 v12, v141 offset:200
	ds_read_b32 v11, v141 offset:76
	ds_read_b32 v13, v141 offset:204
	ds_read_b32 v6, v141 offset:96
	ds_read_b32 v8, v141 offset:224
	ds_read_b32 v7, v141 offset:100
	ds_read_b32 v9, v141 offset:228
	ds_read_b32 v2, v141 offset:104
	ds_read_b32 v4, v141 offset:232
	ds_read_b32 v157, v141 offset:108
	ds_read_b32 v158, v141 offset:236
	s_waitcnt lgkmcnt(0)
	v_fmac_f32_e32 v5, 0x3e38aa3b, v65
	v_fmac_f32_e32 v3, 0x3e38aa3b, v64
	v_fmac_f32_e32 v145, 0x3e38aa3b, v67
	v_fmac_f32_e32 v143, 0x3e38aa3b, v66
	v_cndmask_b32_e64 v65, v5, v129, s[10:11]
	v_cndmask_b32_e64 v64, v3, v129, s[6:7]
	v_fmac_f32_e32 v4, 0x3e38aa3b, v62
	v_fmac_f32_e32 v149, 0x3e38aa3b, v69
	v_fmac_f32_e32 v147, 0x3e38aa3b, v68
	v_cndmask_b32_e64 v67, v145, v129, s[22:23]
	v_cndmask_b32_e64 v66, v143, v129, s[16:17]
	v_max_f32_e32 v62, v64, v65
	v_fmac_f32_e32 v9, 0x3e38aa3b, v61
	v_fmac_f32_e32 v8, 0x3e38aa3b, v60
	v_fmac_f32_e32 v153, 0x3e38aa3b, v71
	v_fmac_f32_e32 v151, 0x3e38aa3b, v70
	v_cndmask_b32_e64 v61, v149, v129, s[36:37]
	v_cndmask_b32_e64 v60, v147, v129, s[28:29]
	v_max3_f32 v62, v62, v66, v67
	v_fmac_f32_e32 v13, 0x3e38aa3b, v59
	v_fmac_f32_e32 v12, 0x3e38aa3b, v58
	v_fmac_f32_e32 v15, 0x3e38aa3b, v73
	v_fmac_f32_e32 v14, 0x3e38aa3b, v72
	v_cndmask_b32_e64 v59, v153, v129, s[48:49]
	v_cndmask_b32_e64 v58, v151, v129, s[42:43]
	v_max3_f32 v62, v62, v60, v61
	v_fmac_f32_e32 v11, 0x3e38aa3b, v75
	v_fmac_f32_e32 v10, 0x3e38aa3b, v74
	v_cndmask_b32_e64 v15, v129, v15, s[58:59]
	v_cndmask_b32_e64 v14, v129, v14, s[54:55]
	v_max3_f32 v62, v62, v58, v59
	v_fmac_f32_e32 v7, 0x3e38aa3b, v77
	v_fmac_f32_e32 v6, 0x3e38aa3b, v76
	v_cndmask_b32_e64 v11, v129, v11, s[66:67]
	v_cndmask_b32_e64 v10, v129, v10, s[62:63]
	v_max3_f32 v62, v62, v14, v15
	v_fmac_f32_e32 v2, 0x3e38aa3b, v78
	v_cndmask_b32_e64 v7, v129, v7, s[74:75]
	v_cndmask_b32_e64 v6, v129, v6, s[70:71]
	v_fmac_f32_e32 v157, 0x3e38aa3b, v79
	v_max3_f32 v62, v62, v10, v11
	v_cndmask_b32_e64 v2, v129, v2, s[78:79]
	v_fmac_f32_e32 v142, 0x3e38aa3b, v49
	v_fmac_f32_e32 v117, 0x3e38aa3b, v48
	v_cndmask_b32_e64 v3, v129, v157, s[80:81]
	v_max3_f32 v62, v62, v6, v7
	v_fmac_f32_e32 v146, 0x3e38aa3b, v51
	v_fmac_f32_e32 v144, 0x3e38aa3b, v50
	v_cndmask_b32_e64 v49, v129, v142, s[14:15]
	v_cndmask_b32_e64 v48, v129, v117, s[8:9]
	v_max3_f32 v62, v62, v2, v3
	v_fmac_f32_e32 v150, 0x3e38aa3b, v53
	v_fmac_f32_e32 v148, 0x3e38aa3b, v52
	v_cndmask_b32_e64 v51, v129, v146, s[26:27]
	v_cndmask_b32_e64 v50, v129, v144, s[20:21]
	v_max3_f32 v62, v62, v48, v49
	v_fmac_f32_e32 v154, 0x3e38aa3b, v55
	v_fmac_f32_e32 v152, 0x3e38aa3b, v54
	v_cndmask_b32_e64 v53, v129, v150, s[40:41]
	v_cndmask_b32_e64 v52, v129, v148, s[34:35]
	v_max3_f32 v62, v62, v50, v51
	v_fmac_f32_e32 v156, 0x3e38aa3b, v57
	v_fmac_f32_e32 v155, 0x3e38aa3b, v56
	v_cndmask_b32_e64 v55, v129, v154, s[52:53]
	v_cndmask_b32_e64 v54, v129, v152, s[46:47]
	v_max3_f32 v62, v62, v52, v53
	v_cndmask_b32_e64 v57, v129, v156, s[60:61]
	v_cndmask_b32_e64 v56, v129, v155, s[56:57]
	v_max3_f32 v62, v62, v54, v55
	v_and_b32_e32 v68, 64, v197
	v_cndmask_b32_e64 v13, v129, v13, s[68:69]
	v_cndmask_b32_e64 v12, v129, v12, s[64:65]
	v_fmac_f32_e32 v158, 0x3e38aa3b, v63
	v_max3_f32 v62, v62, v56, v57
	v_xor_b32_e32 v63, 32, v197
	v_add_u32_e32 v68, 64, v68
	v_cndmask_b32_e64 v9, v129, v9, s[76:77]
	v_cndmask_b32_e64 v8, v129, v8, s[72:73]
	v_max3_f32 v62, v62, v12, v13
	v_cmp_lt_i32_e32 vcc, v63, v68
	v_cndmask_b32_e64 v4, v129, v4, s[82:83]
	v_cndmask_b32_e64 v5, v129, v158, s[84:85]
	v_max3_f32 v62, v62, v8, v9
	v_cndmask_b32_e32 v63, v197, v63, vcc
	v_max3_f32 v62, v62, v4, v5
	v_lshlrev_b32_e32 v63, 2, v63
	ds_bpermute_b32 v63, v63, v62
	s_waitcnt lgkmcnt(0)
	v_max_f32_e32 v63, v63, v63
	v_max_f32_e32 v62, v62, v63
	v_sub_f32_e32 v63, v62, v124
	v_cmp_lt_f32_e32 vcc, s0, v63
	s_cbranch_vccz .LBB0_359
	v_max_f32_e32 v62, v62, v62
	v_max_f32_e32 v63, v124, v124
	v_max_f32_e32 v63, v63, v62
	v_sub_f32_e32 v62, v124, v63
	v_exp_f32_e32 v62, v62
	v_mov_b32_e32 v124, v63
	v_pk_mul_f32 v[46:47], v[46:47], v[62:63] op_sel_hi:[1,0]
	v_pk_mul_f32 v[44:45], v[44:45], v[62:63] op_sel_hi:[1,0]
	v_pk_mul_f32 v[42:43], v[42:43], v[62:63] op_sel_hi:[1,0]
	v_pk_mul_f32 v[40:41], v[40:41], v[62:63] op_sel_hi:[1,0]
	v_pk_mul_f32 v[38:39], v[38:39], v[62:63] op_sel_hi:[1,0]
	v_pk_mul_f32 v[36:37], v[36:37], v[62:63] op_sel_hi:[1,0]
	v_pk_mul_f32 v[34:35], v[34:35], v[62:63] op_sel_hi:[1,0]
	v_pk_mul_f32 v[32:33], v[32:33], v[62:63] op_sel_hi:[1,0]
	v_pk_mul_f32 v[30:31], v[30:31], v[62:63] op_sel_hi:[1,0]
	v_pk_mul_f32 v[28:29], v[28:29], v[62:63] op_sel_hi:[1,0]
	v_pk_mul_f32 v[26:27], v[26:27], v[62:63] op_sel_hi:[1,0]
	v_pk_mul_f32 v[24:25], v[24:25], v[62:63] op_sel_hi:[1,0]
	v_pk_mul_f32 v[22:23], v[22:23], v[62:63] op_sel_hi:[1,0]
	v_pk_mul_f32 v[20:21], v[20:21], v[62:63] op_sel_hi:[1,0]
	v_pk_mul_f32 v[18:19], v[18:19], v[62:63] op_sel_hi:[1,0]
	v_pk_mul_f32 v[16:17], v[16:17], v[62:63] op_sel_hi:[1,0]
	v_mul_f32_e32 v140, v140, v62
